# barrier leader publishes the XCD generation word before its own L1 invalidate (acquire moved after the XGEN add)
# speedup vs baseline: 1.0014x; 1.0014x over previous
; __device__ __forceinline__ unsigned xb_ld(unsigned* p)              { return __hip_atomic_load(p, __ATOMIC_RELAXED, __HIP_MEMORY_SCOPE_AGENT); }
; __device__ __forceinline__ unsigned xb_add(unsigned* p, unsigned v) { return __hip_atomic_fetch_add(p, v, __ATOMIC_RELAXED, __HIP_MEMORY_SCOPE_AGENT); }
; #define XB_SPIN(cond, bar) do { unsigned _sp = 0; while (cond) { __builtin_amdgcn_s_sleep(1); \
;     if ((++_sp & 255u) == 0u) { if (xb_ld(&(bar)[XB_TMO])) break; if (_sp > XB_SPIN_CAP) { atomicAdd(&(bar)[XB_TMO], 1u); break; } } } } while (0)
; __device__ __forceinline__ void xcd_barrier(const XcdBarrier& b) {
;     ...
;             __builtin_amdgcn_fence(__ATOMIC_RELEASE, "agent");
;             asm volatile("s_waitcnt vmcnt(0)" ::: "memory");
;             const unsigned og = xb_add(&bar[XB_TOP], 1u);
;             const unsigned tg = og / nx;
;             if (og + 1u == (tg + 1u) * nx) xb_add(&bar[XB_TOPGEN], 1u);
;             else XB_SPIN(xb_ld(&bar[XB_TOPGEN]) == tg, bar);
;             __builtin_amdgcn_fence(__ATOMIC_ACQUIRE, "agent");
;             xb_add(&bar[XB_XGEN(b.x)], 1u);
;             asm volatile("s_waitcnt vmcnt(0)" ::: "memory");
.LBB0_90:
	s_or_b64 exec, exec, s[8:9]
	s_mov_b64 s[8:9], exec
	v_mbcnt_lo_u32_b32 v1, s8, 0
	v_mbcnt_hi_u32_b32 v1, s9, v1
	v_cmp_eq_u32_e32 vcc, 0, v1
	s_waitcnt vmcnt(0)
	s_and_saveexec_b64 s[10:11], vcc
	s_cbranch_execz .LBB0_92
	s_bcnt1_i32_b64 s8, s[8:9]
	v_mov_b32_e32 v1, 0x2000
	v_mov_b32_e32 v2, s8
	global_atomic_add v1, v2, s[6:7] offset:1024
.LBB0_92:
	s_or_b64 exec, exec, s[10:11]
	buffer_inv sc1
	s_waitcnt vmcnt(0)

; __device__ __forceinline__ unsigned xb_ld(unsigned* p)              { return __hip_atomic_load(p, __ATOMIC_RELAXED, __HIP_MEMORY_SCOPE_AGENT); }
; __device__ __forceinline__ unsigned xb_add(unsigned* p, unsigned v) { return __hip_atomic_fetch_add(p, v, __ATOMIC_RELAXED, __HIP_MEMORY_SCOPE_AGENT); }
; #define XB_SPIN(cond, bar) do { unsigned _sp = 0; while (cond) { __builtin_amdgcn_s_sleep(1); \
;     if ((++_sp & 255u) == 0u) { if (xb_ld(&(bar)[XB_TMO])) break; if (_sp > XB_SPIN_CAP) { atomicAdd(&(bar)[XB_TMO], 1u); break; } } } } while (0)
; __device__ __forceinline__ void xcd_barrier(const XcdBarrier& b) {
;     ...
;             __builtin_amdgcn_fence(__ATOMIC_RELEASE, "agent");
;             asm volatile("s_waitcnt vmcnt(0)" ::: "memory");
;             const unsigned og = xb_add(&bar[XB_TOP], 1u);
;             const unsigned tg = og / nx;
;             if (og + 1u == (tg + 1u) * nx) xb_add(&bar[XB_TOPGEN], 1u);
;             else XB_SPIN(xb_ld(&bar[XB_TOPGEN]) == tg, bar);
;             __builtin_amdgcn_fence(__ATOMIC_ACQUIRE, "agent");
;             xb_add(&bar[XB_XGEN(b.x)], 1u);
;             asm volatile("s_waitcnt vmcnt(0)" ::: "memory");
.LBB0_174:
	s_or_b64 exec, exec, s[6:7]
	s_mov_b64 s[6:7], exec
	v_mbcnt_lo_u32_b32 v1, s6, 0
	v_mbcnt_hi_u32_b32 v1, s7, v1
	v_cmp_eq_u32_e32 vcc, 0, v1
	s_waitcnt vmcnt(0)
	s_and_saveexec_b64 s[8:9], vcc
	s_cbranch_execz .LBB0_176
	s_bcnt1_i32_b64 s6, s[6:7]
	v_mov_b32_e32 v1, 0x2000
	v_mov_b32_e32 v2, s6
	global_atomic_add v1, v2, s[4:5] offset:1024
.LBB0_176:
	s_or_b64 exec, exec, s[8:9]
	buffer_inv sc1
	s_waitcnt vmcnt(0)

; __device__ __forceinline__ unsigned xb_ld(unsigned* p)              { return __hip_atomic_load(p, __ATOMIC_RELAXED, __HIP_MEMORY_SCOPE_AGENT); }
; __device__ __forceinline__ unsigned xb_add(unsigned* p, unsigned v) { return __hip_atomic_fetch_add(p, v, __ATOMIC_RELAXED, __HIP_MEMORY_SCOPE_AGENT); }
; #define XB_SPIN(cond, bar) do { unsigned _sp = 0; while (cond) { __builtin_amdgcn_s_sleep(1); \
;     if ((++_sp & 255u) == 0u) { if (xb_ld(&(bar)[XB_TMO])) break; if (_sp > XB_SPIN_CAP) { atomicAdd(&(bar)[XB_TMO], 1u); break; } } } } while (0)
; __device__ __forceinline__ void xcd_barrier(const XcdBarrier& b) {
;     ...
;             __builtin_amdgcn_fence(__ATOMIC_RELEASE, "agent");
;             asm volatile("s_waitcnt vmcnt(0)" ::: "memory");
;             const unsigned og = xb_add(&bar[XB_TOP], 1u);
;             const unsigned tg = og / nx;
;             if (og + 1u == (tg + 1u) * nx) xb_add(&bar[XB_TOPGEN], 1u);
;             else XB_SPIN(xb_ld(&bar[XB_TOPGEN]) == tg, bar);
;             __builtin_amdgcn_fence(__ATOMIC_ACQUIRE, "agent");
;             xb_add(&bar[XB_XGEN(b.x)], 1u);
;             asm volatile("s_waitcnt vmcnt(0)" ::: "memory");
.LBB0_244:
	s_or_b64 exec, exec, s[2:3]
	s_mov_b64 s[2:3], exec
	v_mbcnt_lo_u32_b32 v2, s2, 0
	v_mbcnt_hi_u32_b32 v2, s3, v2
	v_cmp_eq_u32_e32 vcc, 0, v2
	s_waitcnt vmcnt(0)
	s_and_saveexec_b64 s[4:5], vcc
	s_cbranch_execz .LBB0_246
	s_bcnt1_i32_b64 s2, s[2:3]
	v_mov_b32_e32 v2, s2
	v_readlane_b32 s2, v251, 30
	v_readlane_b32 s3, v251, 31
	s_nop 4
	global_atomic_add v99, v2, s[2:3]
.LBB0_246:
	s_or_b64 exec, exec, s[4:5]
	buffer_inv sc1
	s_waitcnt vmcnt(0)

; __device__ __forceinline__ unsigned xb_ld(unsigned* p)              { return __hip_atomic_load(p, __ATOMIC_RELAXED, __HIP_MEMORY_SCOPE_AGENT); }
; __device__ __forceinline__ unsigned xb_add(unsigned* p, unsigned v) { return __hip_atomic_fetch_add(p, v, __ATOMIC_RELAXED, __HIP_MEMORY_SCOPE_AGENT); }
; #define XB_SPIN(cond, bar) do { unsigned _sp = 0; while (cond) { __builtin_amdgcn_s_sleep(1); \
;     if ((++_sp & 255u) == 0u) { if (xb_ld(&(bar)[XB_TMO])) break; if (_sp > XB_SPIN_CAP) { atomicAdd(&(bar)[XB_TMO], 1u); break; } } } } while (0)
; __device__ __forceinline__ void xcd_barrier(const XcdBarrier& b) {
;     ...
;             __builtin_amdgcn_fence(__ATOMIC_RELEASE, "agent");
;             asm volatile("s_waitcnt vmcnt(0)" ::: "memory");
;             const unsigned og = xb_add(&bar[XB_TOP], 1u);
;             const unsigned tg = og / nx;
;             if (og + 1u == (tg + 1u) * nx) xb_add(&bar[XB_TOPGEN], 1u);
;             else XB_SPIN(xb_ld(&bar[XB_TOPGEN]) == tg, bar);
;             __builtin_amdgcn_fence(__ATOMIC_ACQUIRE, "agent");
;             xb_add(&bar[XB_XGEN(b.x)], 1u);
;             asm volatile("s_waitcnt vmcnt(0)" ::: "memory");
.LBB0_620:
	s_or_b64 exec, exec, s[4:5]
	s_mov_b64 s[4:5], exec
	v_mbcnt_lo_u32_b32 v2, s4, 0
	v_mbcnt_hi_u32_b32 v2, s5, v2
	v_cmp_eq_u32_e32 vcc, 0, v2
	s_waitcnt vmcnt(0)
	s_and_saveexec_b64 s[6:7], vcc
	s_cbranch_execz .LBB0_622
	s_bcnt1_i32_b64 s4, s[4:5]
	v_mov_b32_e32 v2, s4
	v_readlane_b32 s4, v251, 30
	v_readlane_b32 s5, v251, 31
	s_nop 4
	global_atomic_add v99, v2, s[4:5]
.LBB0_622:
	s_or_b64 exec, exec, s[6:7]
	buffer_inv sc1
	s_waitcnt vmcnt(0)

; __device__ __forceinline__ unsigned xb_add(unsigned* p, unsigned v) { return __hip_atomic_fetch_add(p, v, __ATOMIC_RELAXED, __HIP_MEMORY_SCOPE_AGENT); }
; __device__ __forceinline__ void xcd_barrier(const XcdBarrier& b) {
;     ...
;             __builtin_amdgcn_fence(__ATOMIC_ACQUIRE, "agent");
;             xb_add(&bar[XB_XGEN(b.x)], 1u);
;             asm volatile("s_waitcnt vmcnt(0)" ::: "memory");
.Lgb_fast0:
	v_readlane_b32 s2, v252, 42
	v_readlane_b32 s3, v252, 43
	s_waitcnt vmcnt(0)
	s_nop 3
	global_atomic_add v99, v215, s[2:3]
	buffer_inv sc1
	s_waitcnt vmcnt(0)

; __device__ __forceinline__ unsigned xb_add(unsigned* p, unsigned v) { return __hip_atomic_fetch_add(p, v, __ATOMIC_RELAXED, __HIP_MEMORY_SCOPE_AGENT); }
; __device__ __forceinline__ void xcd_barrier(const XcdBarrier& b) {
;     ...
;             __builtin_amdgcn_fence(__ATOMIC_ACQUIRE, "agent");
;             xb_add(&bar[XB_XGEN(b.x)], 1u);
;             asm volatile("s_waitcnt vmcnt(0)" ::: "memory");
.Lgb_fast5:
	v_readlane_b32 s4, v252, 42
	v_readlane_b32 s5, v252, 43
	s_waitcnt vmcnt(0)
	s_nop 3
	global_atomic_add v99, v215, s[4:5]
	buffer_inv sc1
	s_waitcnt vmcnt(0)
